# P1 h0 row loop unrolled by two with the register sets swapping roles (no end-of-row copy), waits cover only the current row's loads; on top of the LN2 fill batching
# speedup vs baseline: 1.0025x; 1.0025x over previous
.LBB0_181:
	s_add_u32 s20, s18, 8
	s_addc_u32 s21, s19, 0
	s_cmp_ge_i32 s20, s26
	s_cselect_b64 s[22:23], -1, 0
	s_cmp_lt_i32 s20, s26
	s_cbranch_scc0 .Lmy_h0_even_last
	s_add_i32 s19, s18, 0xfffff008
	s_cmpk_lt_i32 s18, 0xff8
	s_cselect_b32 s25, s21, 0
	s_cselect_b32 s24, s20, s19
	s_cselect_b32 s19, s9, s11
	s_cselect_b32 s28, s8, s10
	s_lshl_b64 s[24:25], s[24:25], 13
	s_add_u32 s24, s28, s24
	s_addc_u32 s25, s19, s25
	v_lshl_add_u64 v[32:33], s[24:25], 0, v[64:65]
	global_load_dwordx4 v[0:3], v64, s[24:25] offset:16 nt
	global_load_dwordx4 v[4:7], v64, s[24:25] nt
	global_load_dwordx4 v[12:15], v64, s[24:25] offset:2064 nt
	global_load_dwordx4 v[16:19], v64, s[24:25] offset:2048 nt
	v_add_co_u32_e32 v70, vcc, s27, v32
	v_lshl_add_u64 v[34:35], v[32:33], 0, s[12:13]
	s_nop 0
	v_addc_co_u32_e32 v71, vcc, 0, v33, vcc
	global_load_dwordx4 v[24:27], v[70:71], off nt
	global_load_dwordx4 v[20:23], v[34:35], off offset:16 nt
	v_lshl_add_u64 v[72:73], v[32:33], 0, s[14:15]
	global_load_dwordx4 v[36:39], v[70:71], off offset:2048 nt
	global_load_dwordx4 v[32:35], v[72:73], off offset:16 nt
	s_add_i32 s19, s18, 0xfffff000
	s_lshr_b32 s19, s19, 10
	s_add_i32 s19, s19, 1
	s_cmpk_gt_i32 s18, 0xfff
	s_cselect_b32 s18, s19, 0
	s_sub_i32 s18, s18, s3
	v_lshl_add_u32 v69, s18, 14, v68
	ds_read_b128 v[70:73], v69 offset:8192
	ds_read_b128 v[74:77], v69
	ds_read_b128 v[78:81], v69 offset:8208
	s_andn2_b64 vcc, exec, s[22:23]
	s_mov_b64 s[18:19], s[20:21]
	s_waitcnt lgkmcnt(2)
	v_pk_add_f32 v[82:83], v[72:73], 1.0 op_sel_hi:[1,0]
	v_pk_add_f32 v[84:85], v[70:71], 1.0 op_sel_hi:[1,0]
	ds_read_b128 v[70:73], v69 offset:16
	s_waitcnt vmcnt(15) lgkmcnt(2)
	v_pk_fma_f32 v[62:63], v[62:63], v[82:83], v[76:77]
	v_pk_fma_f32 v[60:61], v[60:61], v[84:85], v[74:75]
	s_waitcnt lgkmcnt(1)
	v_pk_add_f32 v[74:75], v[80:81], 1.0 op_sel_hi:[1,0]
	v_pk_add_f32 v[76:77], v[78:79], 1.0 op_sel_hi:[1,0]
	s_waitcnt vmcnt(14) lgkmcnt(0)
	v_pk_fma_f32 v[72:73], v[58:59], v[74:75], v[72:73]
	v_pk_fma_f32 v[58:59], v[56:57], v[76:77], v[70:71]
	v_cvt_pk_bf16_f32 v56, v60, v61
	v_cvt_pk_bf16_f32 v57, v62, v63
	ds_read_b128 v[60:63], v69 offset:10240
	v_cvt_pk_bf16_f32 v58, v58, v59
	v_cvt_pk_bf16_f32 v59, v72, v73
	global_store_dwordx4 v[66:67], v[56:59], off
	ds_read_b128 v[56:59], v69 offset:2048
	ds_read_b128 v[70:73], v69 offset:10256
	s_waitcnt lgkmcnt(2)
	v_pk_add_f32 v[74:75], v[62:63], 1.0 op_sel_hi:[1,0]
	v_pk_add_f32 v[76:77], v[60:61], 1.0 op_sel_hi:[1,0]
	ds_read_b128 v[60:63], v69 offset:2064
	s_waitcnt vmcnt(14) lgkmcnt(2)
	v_pk_fma_f32 v[54:55], v[54:55], v[74:75], v[58:59]
	v_pk_fma_f32 v[52:53], v[52:53], v[76:77], v[56:57]
	s_waitcnt lgkmcnt(1)
	v_pk_add_f32 v[56:57], v[72:73], 1.0 op_sel_hi:[1,0]
	v_pk_add_f32 v[58:59], v[70:71], 1.0 op_sel_hi:[1,0]
	s_waitcnt vmcnt(13) lgkmcnt(0)
	v_pk_fma_f32 v[56:57], v[50:51], v[56:57], v[62:63]
	v_pk_fma_f32 v[50:51], v[48:49], v[58:59], v[60:61]
	v_cvt_pk_bf16_f32 v48, v52, v53
	v_cvt_pk_bf16_f32 v49, v54, v55
	ds_read_b128 v[52:55], v69 offset:12288
	v_cvt_pk_bf16_f32 v50, v50, v51
	v_cvt_pk_bf16_f32 v51, v56, v57
	global_store_dwordx4 v[66:67], v[48:51], off offset:1024
	ds_read_b128 v[48:51], v69 offset:4096
	ds_read_b128 v[56:59], v69 offset:12304
	s_waitcnt lgkmcnt(2)
	v_pk_add_f32 v[60:61], v[54:55], 1.0 op_sel_hi:[1,0]
	v_pk_add_f32 v[62:63], v[52:53], 1.0 op_sel_hi:[1,0]
	ds_read_b128 v[52:55], v69 offset:4112
	s_waitcnt vmcnt(13) lgkmcnt(2)
	v_pk_fma_f32 v[46:47], v[46:47], v[60:61], v[50:51]
	v_pk_fma_f32 v[44:45], v[44:45], v[62:63], v[48:49]
	s_waitcnt lgkmcnt(1)
	v_pk_add_f32 v[48:49], v[58:59], 1.0 op_sel_hi:[1,0]
	v_pk_add_f32 v[50:51], v[56:57], 1.0 op_sel_hi:[1,0]
	s_waitcnt vmcnt(12) lgkmcnt(0)
	v_pk_fma_f32 v[48:49], v[42:43], v[48:49], v[54:55]
	v_pk_fma_f32 v[42:43], v[40:41], v[50:51], v[52:53]
	v_cvt_pk_bf16_f32 v40, v44, v45
	v_cvt_pk_bf16_f32 v41, v46, v47
	ds_read_b128 v[44:47], v69 offset:14336
	v_cvt_pk_bf16_f32 v42, v42, v43
	v_cvt_pk_bf16_f32 v43, v48, v49
	global_store_dwordx4 v[66:67], v[40:43], off offset:2048
	ds_read_b128 v[40:43], v69 offset:6144
	ds_read_b128 v[48:51], v69 offset:14352
	s_waitcnt lgkmcnt(2)
	v_pk_add_f32 v[52:53], v[46:47], 1.0 op_sel_hi:[1,0]
	v_pk_add_f32 v[54:55], v[44:45], 1.0 op_sel_hi:[1,0]
	ds_read_b128 v[44:47], v69 offset:6160
	s_waitcnt vmcnt(12) lgkmcnt(2)
	v_pk_fma_f32 v[30:31], v[30:31], v[52:53], v[42:43]
	v_pk_fma_f32 v[28:29], v[28:29], v[54:55], v[40:41]
	s_waitcnt lgkmcnt(1)
	v_pk_add_f32 v[40:41], v[50:51], 1.0 op_sel_hi:[1,0]
	v_pk_add_f32 v[42:43], v[48:49], 1.0 op_sel_hi:[1,0]
	s_waitcnt vmcnt(11) lgkmcnt(0)
	v_pk_fma_f32 v[40:41], v[10:11], v[40:41], v[46:47]
	v_pk_fma_f32 v[10:11], v[8:9], v[42:43], v[44:45]
	v_cvt_pk_bf16_f32 v8, v28, v29
	v_cvt_pk_bf16_f32 v9, v30, v31
	v_cvt_pk_bf16_f32 v10, v10, v11
	v_cvt_pk_bf16_f32 v11, v40, v41
	global_store_dwordx4 v[66:67], v[8:11], off offset:3072
	v_lshl_add_u64 v[66:67], v[66:67], 0, s[16:17]
	s_add_u32 s20, s18, 8
	s_addc_u32 s21, s19, 0
	s_cmp_ge_i32 s20, s26
	s_cselect_b64 s[22:23], -1, 0
	s_cmp_lt_i32 s20, s26
	s_cbranch_scc0 .Lmy_h0_odd_last
	s_add_i32 s19, s18, 0xfffff008
	s_cmpk_lt_i32 s18, 0xff8
	s_cselect_b32 s25, s21, 0
	s_cselect_b32 s24, s20, s19
	s_cselect_b32 s19, s9, s11
	s_cselect_b32 s28, s8, s10
	s_lshl_b64 s[24:25], s[24:25], 13
	s_add_u32 s24, s28, s24
	s_addc_u32 s25, s19, s25
	v_lshl_add_u64 v[8:9], s[24:25], 0, v[64:65]
	global_load_dwordx4 v[56:59], v64, s[24:25] offset:16 nt
	global_load_dwordx4 v[60:63], v64, s[24:25] nt
	global_load_dwordx4 v[48:51], v64, s[24:25] offset:2064 nt
	global_load_dwordx4 v[52:55], v64, s[24:25] offset:2048 nt
	v_add_co_u32_e32 v70, vcc, s27, v8
	v_lshl_add_u64 v[10:11], v[8:9], 0, s[12:13]
	s_nop 0
	v_addc_co_u32_e32 v71, vcc, 0, v9, vcc
	global_load_dwordx4 v[44:47], v[70:71], off nt
	global_load_dwordx4 v[40:43], v[10:11], off offset:16 nt
	v_lshl_add_u64 v[72:73], v[8:9], 0, s[14:15]
	global_load_dwordx4 v[28:31], v[70:71], off offset:2048 nt
	global_load_dwordx4 v[8:11], v[72:73], off offset:16 nt
	s_add_i32 s19, s18, 0xfffff000
	s_lshr_b32 s19, s19, 10
	s_add_i32 s19, s19, 1
	s_cmpk_gt_i32 s18, 0xfff
	s_cselect_b32 s18, s19, 0
	s_sub_i32 s18, s18, s3
	v_lshl_add_u32 v69, s18, 14, v68
	ds_read_b128 v[70:73], v69 offset:8192
	ds_read_b128 v[74:77], v69
	ds_read_b128 v[78:81], v69 offset:8208
	s_andn2_b64 vcc, exec, s[22:23]
	s_mov_b64 s[18:19], s[20:21]
	s_waitcnt lgkmcnt(2)
	v_pk_add_f32 v[82:83], v[72:73], 1.0 op_sel_hi:[1,0]
	v_pk_add_f32 v[84:85], v[70:71], 1.0 op_sel_hi:[1,0]
	ds_read_b128 v[70:73], v69 offset:16
	s_waitcnt vmcnt(15) lgkmcnt(2)
	v_pk_fma_f32 v[6:7], v[6:7], v[82:83], v[76:77]
	v_pk_fma_f32 v[4:5], v[4:5], v[84:85], v[74:75]
	s_waitcnt lgkmcnt(1)
	v_pk_add_f32 v[74:75], v[80:81], 1.0 op_sel_hi:[1,0]
	v_pk_add_f32 v[76:77], v[78:79], 1.0 op_sel_hi:[1,0]
	s_waitcnt vmcnt(14) lgkmcnt(0)
	v_pk_fma_f32 v[72:73], v[2:3], v[74:75], v[72:73]
	v_pk_fma_f32 v[2:3], v[0:1], v[76:77], v[70:71]
	v_cvt_pk_bf16_f32 v0, v4, v5
	v_cvt_pk_bf16_f32 v1, v6, v7
	ds_read_b128 v[4:7], v69 offset:10240
	v_cvt_pk_bf16_f32 v2, v2, v3
	v_cvt_pk_bf16_f32 v3, v72, v73
	global_store_dwordx4 v[66:67], v[0:3], off
	ds_read_b128 v[0:3], v69 offset:2048
	ds_read_b128 v[70:73], v69 offset:10256
	s_waitcnt lgkmcnt(2)
	v_pk_add_f32 v[74:75], v[6:7], 1.0 op_sel_hi:[1,0]
	v_pk_add_f32 v[76:77], v[4:5], 1.0 op_sel_hi:[1,0]
	ds_read_b128 v[4:7], v69 offset:2064
	s_waitcnt vmcnt(14) lgkmcnt(2)
	v_pk_fma_f32 v[18:19], v[18:19], v[74:75], v[2:3]
	v_pk_fma_f32 v[16:17], v[16:17], v[76:77], v[0:1]
	s_waitcnt lgkmcnt(1)
	v_pk_add_f32 v[0:1], v[72:73], 1.0 op_sel_hi:[1,0]
	v_pk_add_f32 v[2:3], v[70:71], 1.0 op_sel_hi:[1,0]
	s_waitcnt vmcnt(13) lgkmcnt(0)
	v_pk_fma_f32 v[0:1], v[14:15], v[0:1], v[6:7]
	v_pk_fma_f32 v[14:15], v[12:13], v[2:3], v[4:5]
	v_cvt_pk_bf16_f32 v12, v16, v17
	v_cvt_pk_bf16_f32 v13, v18, v19
	ds_read_b128 v[16:19], v69 offset:12288
	v_cvt_pk_bf16_f32 v14, v14, v15
	v_cvt_pk_bf16_f32 v15, v0, v1
	global_store_dwordx4 v[66:67], v[12:15], off offset:1024
	ds_read_b128 v[12:15], v69 offset:4096
	ds_read_b128 v[0:3], v69 offset:12304
	s_waitcnt lgkmcnt(2)
	v_pk_add_f32 v[4:5], v[18:19], 1.0 op_sel_hi:[1,0]
	v_pk_add_f32 v[6:7], v[16:17], 1.0 op_sel_hi:[1,0]
	ds_read_b128 v[16:19], v69 offset:4112
	s_waitcnt vmcnt(13) lgkmcnt(2)
	v_pk_fma_f32 v[26:27], v[26:27], v[4:5], v[14:15]
	v_pk_fma_f32 v[24:25], v[24:25], v[6:7], v[12:13]
	s_waitcnt lgkmcnt(1)
	v_pk_add_f32 v[12:13], v[2:3], 1.0 op_sel_hi:[1,0]
	v_pk_add_f32 v[14:15], v[0:1], 1.0 op_sel_hi:[1,0]
	s_waitcnt vmcnt(12) lgkmcnt(0)
	v_pk_fma_f32 v[12:13], v[22:23], v[12:13], v[18:19]
	v_pk_fma_f32 v[22:23], v[20:21], v[14:15], v[16:17]
	v_cvt_pk_bf16_f32 v20, v24, v25
	v_cvt_pk_bf16_f32 v21, v26, v27
	ds_read_b128 v[24:27], v69 offset:14336
	v_cvt_pk_bf16_f32 v22, v22, v23
	v_cvt_pk_bf16_f32 v23, v12, v13
	global_store_dwordx4 v[66:67], v[20:23], off offset:2048
	ds_read_b128 v[20:23], v69 offset:6144
	ds_read_b128 v[12:15], v69 offset:14352
	s_waitcnt lgkmcnt(2)
	v_pk_add_f32 v[16:17], v[26:27], 1.0 op_sel_hi:[1,0]
	v_pk_add_f32 v[18:19], v[24:25], 1.0 op_sel_hi:[1,0]
	ds_read_b128 v[24:27], v69 offset:6160
	s_waitcnt vmcnt(12) lgkmcnt(2)
	v_pk_fma_f32 v[38:39], v[38:39], v[16:17], v[22:23]
	v_pk_fma_f32 v[36:37], v[36:37], v[18:19], v[20:21]
	s_waitcnt lgkmcnt(1)
	v_pk_add_f32 v[20:21], v[14:15], 1.0 op_sel_hi:[1,0]
	v_pk_add_f32 v[22:23], v[12:13], 1.0 op_sel_hi:[1,0]
	s_waitcnt vmcnt(11) lgkmcnt(0)
	v_pk_fma_f32 v[20:21], v[34:35], v[20:21], v[26:27]
	v_pk_fma_f32 v[34:35], v[32:33], v[22:23], v[24:25]
	v_cvt_pk_bf16_f32 v32, v36, v37
	v_cvt_pk_bf16_f32 v33, v38, v39
	v_cvt_pk_bf16_f32 v34, v34, v35
	v_cvt_pk_bf16_f32 v35, v20, v21
	global_store_dwordx4 v[66:67], v[32:35], off offset:3072
	v_lshl_add_u64 v[66:67], v[66:67], 0, s[16:17]
	s_branch .LBB0_181
.Lmy_h0_even_last:
	s_add_i32 s19, s18, 0xfffff000
	s_lshr_b32 s19, s19, 10
	s_add_i32 s19, s19, 1
	s_cmpk_gt_i32 s18, 0xfff
	s_cselect_b32 s18, s19, 0
	s_sub_i32 s18, s18, s3
	v_lshl_add_u32 v69, s18, 14, v68
	ds_read_b128 v[70:73], v69 offset:8192
	ds_read_b128 v[74:77], v69
	ds_read_b128 v[78:81], v69 offset:8208
	s_andn2_b64 vcc, exec, s[22:23]
	s_mov_b64 s[18:19], s[20:21]
	s_waitcnt lgkmcnt(2)
	v_pk_add_f32 v[82:83], v[72:73], 1.0 op_sel_hi:[1,0]
	v_pk_add_f32 v[84:85], v[70:71], 1.0 op_sel_hi:[1,0]
	ds_read_b128 v[70:73], v69 offset:16
	s_waitcnt vmcnt(7) lgkmcnt(2)
	v_pk_fma_f32 v[62:63], v[62:63], v[82:83], v[76:77]
	v_pk_fma_f32 v[60:61], v[60:61], v[84:85], v[74:75]
	s_waitcnt lgkmcnt(1)
	v_pk_add_f32 v[74:75], v[80:81], 1.0 op_sel_hi:[1,0]
	v_pk_add_f32 v[76:77], v[78:79], 1.0 op_sel_hi:[1,0]
	s_waitcnt vmcnt(6) lgkmcnt(0)
	v_pk_fma_f32 v[72:73], v[58:59], v[74:75], v[72:73]
	v_pk_fma_f32 v[58:59], v[56:57], v[76:77], v[70:71]
	v_cvt_pk_bf16_f32 v56, v60, v61
	v_cvt_pk_bf16_f32 v57, v62, v63
	ds_read_b128 v[60:63], v69 offset:10240
	v_cvt_pk_bf16_f32 v58, v58, v59
	v_cvt_pk_bf16_f32 v59, v72, v73
	global_store_dwordx4 v[66:67], v[56:59], off
	ds_read_b128 v[56:59], v69 offset:2048
	ds_read_b128 v[70:73], v69 offset:10256
	s_waitcnt lgkmcnt(2)
	v_pk_add_f32 v[74:75], v[62:63], 1.0 op_sel_hi:[1,0]
	v_pk_add_f32 v[76:77], v[60:61], 1.0 op_sel_hi:[1,0]
	ds_read_b128 v[60:63], v69 offset:2064
	s_waitcnt vmcnt(6) lgkmcnt(2)
	v_pk_fma_f32 v[54:55], v[54:55], v[74:75], v[58:59]
	v_pk_fma_f32 v[52:53], v[52:53], v[76:77], v[56:57]
	s_waitcnt lgkmcnt(1)
	v_pk_add_f32 v[56:57], v[72:73], 1.0 op_sel_hi:[1,0]
	v_pk_add_f32 v[58:59], v[70:71], 1.0 op_sel_hi:[1,0]
	s_waitcnt vmcnt(5) lgkmcnt(0)
	v_pk_fma_f32 v[56:57], v[50:51], v[56:57], v[62:63]
	v_pk_fma_f32 v[50:51], v[48:49], v[58:59], v[60:61]
	v_cvt_pk_bf16_f32 v48, v52, v53
	v_cvt_pk_bf16_f32 v49, v54, v55
	ds_read_b128 v[52:55], v69 offset:12288
	v_cvt_pk_bf16_f32 v50, v50, v51
	v_cvt_pk_bf16_f32 v51, v56, v57
	global_store_dwordx4 v[66:67], v[48:51], off offset:1024
	ds_read_b128 v[48:51], v69 offset:4096
	ds_read_b128 v[56:59], v69 offset:12304
	s_waitcnt lgkmcnt(2)
	v_pk_add_f32 v[60:61], v[54:55], 1.0 op_sel_hi:[1,0]
	v_pk_add_f32 v[62:63], v[52:53], 1.0 op_sel_hi:[1,0]
	ds_read_b128 v[52:55], v69 offset:4112
	s_waitcnt vmcnt(5) lgkmcnt(2)
	v_pk_fma_f32 v[46:47], v[46:47], v[60:61], v[50:51]
	v_pk_fma_f32 v[44:45], v[44:45], v[62:63], v[48:49]
	s_waitcnt lgkmcnt(1)
	v_pk_add_f32 v[48:49], v[58:59], 1.0 op_sel_hi:[1,0]
	v_pk_add_f32 v[50:51], v[56:57], 1.0 op_sel_hi:[1,0]
	s_waitcnt vmcnt(4) lgkmcnt(0)
	v_pk_fma_f32 v[48:49], v[42:43], v[48:49], v[54:55]
	v_pk_fma_f32 v[42:43], v[40:41], v[50:51], v[52:53]
	v_cvt_pk_bf16_f32 v40, v44, v45
	v_cvt_pk_bf16_f32 v41, v46, v47
	ds_read_b128 v[44:47], v69 offset:14336
	v_cvt_pk_bf16_f32 v42, v42, v43
	v_cvt_pk_bf16_f32 v43, v48, v49
	global_store_dwordx4 v[66:67], v[40:43], off offset:2048
	ds_read_b128 v[40:43], v69 offset:6144
	ds_read_b128 v[48:51], v69 offset:14352
	s_waitcnt lgkmcnt(2)
	v_pk_add_f32 v[52:53], v[46:47], 1.0 op_sel_hi:[1,0]
	v_pk_add_f32 v[54:55], v[44:45], 1.0 op_sel_hi:[1,0]
	ds_read_b128 v[44:47], v69 offset:6160
	s_waitcnt vmcnt(4) lgkmcnt(2)
	v_pk_fma_f32 v[30:31], v[30:31], v[52:53], v[42:43]
	v_pk_fma_f32 v[28:29], v[28:29], v[54:55], v[40:41]
	s_waitcnt lgkmcnt(1)
	v_pk_add_f32 v[40:41], v[50:51], 1.0 op_sel_hi:[1,0]
	v_pk_add_f32 v[42:43], v[48:49], 1.0 op_sel_hi:[1,0]
	s_waitcnt vmcnt(3) lgkmcnt(0)
	v_pk_fma_f32 v[40:41], v[10:11], v[40:41], v[46:47]
	v_pk_fma_f32 v[10:11], v[8:9], v[42:43], v[44:45]
	v_cvt_pk_bf16_f32 v8, v28, v29
	v_cvt_pk_bf16_f32 v9, v30, v31
	v_cvt_pk_bf16_f32 v10, v10, v11
	v_cvt_pk_bf16_f32 v11, v40, v41
	global_store_dwordx4 v[66:67], v[8:11], off offset:3072
	v_lshl_add_u64 v[66:67], v[66:67], 0, s[16:17]
	s_branch .LBB0_185
.Lmy_h0_odd_last:
	s_add_i32 s19, s18, 0xfffff000
	s_lshr_b32 s19, s19, 10
	s_add_i32 s19, s19, 1
	s_cmpk_gt_i32 s18, 0xfff
	s_cselect_b32 s18, s19, 0
	s_sub_i32 s18, s18, s3
	v_lshl_add_u32 v69, s18, 14, v68
	ds_read_b128 v[70:73], v69 offset:8192
	ds_read_b128 v[74:77], v69
	ds_read_b128 v[78:81], v69 offset:8208
	s_andn2_b64 vcc, exec, s[22:23]
	s_mov_b64 s[18:19], s[20:21]
	s_waitcnt lgkmcnt(2)
	v_pk_add_f32 v[82:83], v[72:73], 1.0 op_sel_hi:[1,0]
	v_pk_add_f32 v[84:85], v[70:71], 1.0 op_sel_hi:[1,0]
	ds_read_b128 v[70:73], v69 offset:16
	s_waitcnt vmcnt(7) lgkmcnt(2)
	v_pk_fma_f32 v[6:7], v[6:7], v[82:83], v[76:77]
	v_pk_fma_f32 v[4:5], v[4:5], v[84:85], v[74:75]
	s_waitcnt lgkmcnt(1)
	v_pk_add_f32 v[74:75], v[80:81], 1.0 op_sel_hi:[1,0]
	v_pk_add_f32 v[76:77], v[78:79], 1.0 op_sel_hi:[1,0]
	s_waitcnt vmcnt(6) lgkmcnt(0)
	v_pk_fma_f32 v[72:73], v[2:3], v[74:75], v[72:73]
	v_pk_fma_f32 v[2:3], v[0:1], v[76:77], v[70:71]
	v_cvt_pk_bf16_f32 v0, v4, v5
	v_cvt_pk_bf16_f32 v1, v6, v7
	ds_read_b128 v[4:7], v69 offset:10240
	v_cvt_pk_bf16_f32 v2, v2, v3
	v_cvt_pk_bf16_f32 v3, v72, v73
	global_store_dwordx4 v[66:67], v[0:3], off
	ds_read_b128 v[0:3], v69 offset:2048
	ds_read_b128 v[70:73], v69 offset:10256
	s_waitcnt lgkmcnt(2)
	v_pk_add_f32 v[74:75], v[6:7], 1.0 op_sel_hi:[1,0]
	v_pk_add_f32 v[76:77], v[4:5], 1.0 op_sel_hi:[1,0]
	ds_read_b128 v[4:7], v69 offset:2064
	s_waitcnt vmcnt(6) lgkmcnt(2)
	v_pk_fma_f32 v[18:19], v[18:19], v[74:75], v[2:3]
	v_pk_fma_f32 v[16:17], v[16:17], v[76:77], v[0:1]
	s_waitcnt lgkmcnt(1)
	v_pk_add_f32 v[0:1], v[72:73], 1.0 op_sel_hi:[1,0]
	v_pk_add_f32 v[2:3], v[70:71], 1.0 op_sel_hi:[1,0]
	s_waitcnt vmcnt(5) lgkmcnt(0)
	v_pk_fma_f32 v[0:1], v[14:15], v[0:1], v[6:7]
	v_pk_fma_f32 v[14:15], v[12:13], v[2:3], v[4:5]
	v_cvt_pk_bf16_f32 v12, v16, v17
	v_cvt_pk_bf16_f32 v13, v18, v19
	ds_read_b128 v[16:19], v69 offset:12288
	v_cvt_pk_bf16_f32 v14, v14, v15
	v_cvt_pk_bf16_f32 v15, v0, v1
	global_store_dwordx4 v[66:67], v[12:15], off offset:1024
	ds_read_b128 v[12:15], v69 offset:4096
	ds_read_b128 v[0:3], v69 offset:12304
	s_waitcnt lgkmcnt(2)
	v_pk_add_f32 v[4:5], v[18:19], 1.0 op_sel_hi:[1,0]
	v_pk_add_f32 v[6:7], v[16:17], 1.0 op_sel_hi:[1,0]
	ds_read_b128 v[16:19], v69 offset:4112
	s_waitcnt vmcnt(5) lgkmcnt(2)
	v_pk_fma_f32 v[26:27], v[26:27], v[4:5], v[14:15]
	v_pk_fma_f32 v[24:25], v[24:25], v[6:7], v[12:13]
	s_waitcnt lgkmcnt(1)
	v_pk_add_f32 v[12:13], v[2:3], 1.0 op_sel_hi:[1,0]
	v_pk_add_f32 v[14:15], v[0:1], 1.0 op_sel_hi:[1,0]
	s_waitcnt vmcnt(4) lgkmcnt(0)
	v_pk_fma_f32 v[12:13], v[22:23], v[12:13], v[18:19]
	v_pk_fma_f32 v[22:23], v[20:21], v[14:15], v[16:17]
	v_cvt_pk_bf16_f32 v20, v24, v25
	v_cvt_pk_bf16_f32 v21, v26, v27
	ds_read_b128 v[24:27], v69 offset:14336
	v_cvt_pk_bf16_f32 v22, v22, v23
	v_cvt_pk_bf16_f32 v23, v12, v13
	global_store_dwordx4 v[66:67], v[20:23], off offset:2048
	ds_read_b128 v[20:23], v69 offset:6144
	ds_read_b128 v[12:15], v69 offset:14352
	s_waitcnt lgkmcnt(2)
	v_pk_add_f32 v[16:17], v[26:27], 1.0 op_sel_hi:[1,0]
	v_pk_add_f32 v[18:19], v[24:25], 1.0 op_sel_hi:[1,0]
	ds_read_b128 v[24:27], v69 offset:6160
	s_waitcnt vmcnt(4) lgkmcnt(2)
	v_pk_fma_f32 v[38:39], v[38:39], v[16:17], v[22:23]
	v_pk_fma_f32 v[36:37], v[36:37], v[18:19], v[20:21]
	s_waitcnt lgkmcnt(1)
	v_pk_add_f32 v[20:21], v[14:15], 1.0 op_sel_hi:[1,0]
	v_pk_add_f32 v[22:23], v[12:13], 1.0 op_sel_hi:[1,0]
	s_waitcnt vmcnt(3) lgkmcnt(0)
	v_pk_fma_f32 v[20:21], v[34:35], v[20:21], v[26:27]
	v_pk_fma_f32 v[34:35], v[32:33], v[22:23], v[24:25]
	v_cvt_pk_bf16_f32 v32, v36, v37
	v_cvt_pk_bf16_f32 v33, v38, v39
	v_cvt_pk_bf16_f32 v34, v34, v35
	v_cvt_pk_bf16_f32 v35, v20, v21
	global_store_dwordx4 v[66:67], v[32:35], off offset:3072
	v_lshl_add_u64 v[66:67], v[66:67], 0, s[16:17]
	s_branch .LBB0_185
